# m10_xcd_local_barriers_guarded
# speedup vs baseline: 1.0164x; 1.0139x over previous
; #define LAS __attribute__((address_space(3)))
; __device__ __forceinline__ unsigned xb_add(unsigned* p, unsigned v) { return __hip_atomic_fetch_add(p, v, __ATOMIC_RELAXED, __HIP_MEMORY_SCOPE_AGENT); }
; __device__ __forceinline__ unsigned xb_xcc_id() { return (unsigned)__builtin_amdgcn_s_getreg((3 << 11) | 20) & 0xFu; }
; __device__ __forceinline__ XcdBarrier xcd_barrier_post(unsigned* bar, volatile LAS unsigned* st) {
;     XcdBarrier b; b.bar = bar; b.x = xb_xcc_id(); b.st = st;
;     if (threadIdx.x == 0) (void)xb_add(&bar[XB_XCNT(b.x)], 1u);
;     return b;
; }
; __global__ void __launch_bounds__(512, 2) fwd_kernel(Args a0) {
;     ...
;     volatile LAS unsigned* st = (volatile LAS unsigned*)(lds + LDS_BYTES - 64);
;     if (threadIdx.x < 16) st[threadIdx.x] = 0u;
;     __syncthreads();
;     XcdBarrier bar = xcd_barrier_post((unsigned*)(a0.ws + WS_CTL), st);
.LBB0_2:
	s_load_dwordx2 s[76:77], s[60:61], 0xa8
	v_and_b32_e32 v228, 0x3ff, v0
	v_cmp_gt_u32_e32 vcc, 16, v228
	s_and_saveexec_b64 s[4:5], vcc
	v_lshl_add_u32 v1, v228, 2, 0
	v_add_u32_e32 v1, 0x23fc0, v1
	v_mov_b32_e32 v2, 0
	ds_write_b32 v1, v2
	s_or_b64 exec, exec, s[4:5]
	s_waitcnt lgkmcnt(0)
	s_barrier
	s_add_u32 s6, s0, 0xda00000
	s_getreg_b32 s2, hwreg(HW_REG_XCC_ID, 0, 4)
	s_addc_u32 s7, s1, 0
	s_and_b32 s10, s2, 15
	v_cmp_eq_u32_e64 s[8:9], 0, v228
	s_mov_b64 s[4:5], exec
	s_nop 0
	v_writelane_b32 v253, s8, 3
	s_nop 1
	v_writelane_b32 v253, s9, 4
	s_and_b64 s[8:9], s[4:5], s[8:9]
	s_mov_b64 exec, s[8:9]
	s_cbranch_execz .LBB0_7
	s_mov_b64 s[8:9], exec
	v_mbcnt_lo_u32_b32 v1, s8, 0
	v_mbcnt_hi_u32_b32 v1, s9, v1
	v_cmp_eq_u32_e32 vcc, 0, v1
	s_and_b64 s[12:13], exec, vcc
	s_mov_b64 exec, s[12:13]
	s_cbranch_execz .LBB0_7
	s_lshl_b32 s2, s10, 8
	s_bcnt1_i32_b64 s8, s[8:9]
	v_mov_b32_e32 v1, s2
	v_mov_b32_e32 v2, s8
	global_atomic_add v1, v2, s[6:7] offset:1024
	s_and_b32 s2, s96, 7
	s_lshl_b32 s2, s2, 8
	s_addk_i32 s2, 0x4000
	s_lshl_b32 s8, 1, s10
	v_mov_b32_e32 v3, s2
	v_mov_b32_e32 v4, s8
	global_atomic_or v3, v4, s[6:7]

; __device__ __forceinline__ unsigned xb_ld(unsigned* p)              { return __hip_atomic_load(p, __ATOMIC_RELAXED, __HIP_MEMORY_SCOPE_AGENT); }
; __device__ __forceinline__ unsigned xb_add(unsigned* p, unsigned v) { return __hip_atomic_fetch_add(p, v, __ATOMIC_RELAXED, __HIP_MEMORY_SCOPE_AGENT); }
; #define XB_SPIN(cond, bar) do { unsigned _sp = 0; while (cond) { __builtin_amdgcn_s_sleep(1); \
;     if ((++_sp & 255u) == 0u) { if (xb_ld(&(bar)[XB_TMO])) break; if (_sp > XB_SPIN_CAP) { atomicAdd(&(bar)[XB_TMO], 1u); break; } } } } while (0)
; __device__ __forceinline__ void xcd_barrier(const XcdBarrier& b) {
;     asm volatile("s_waitcnt vmcnt(0)" ::: "memory");
;     __syncthreads();
;     if (threadIdx.x == 0) {
;         unsigned* bar = b.bar;
;         __builtin_amdgcn_s_waitcnt(0);
;         unsigned nloc = b.st[0], nx = b.st[1];
;         if (nloc == 0u) { xcd_barrier_complete(bar, b.x, nloc, nx); b.st[0] = nloc; b.st[1] = nx; }
;         const unsigned old = xb_add(&bar[XB_XSUB(b.x)], 1u);
;         const unsigned gen = old / nloc;
;         if (old + 1u == (gen + 1u) * nloc) {
;             __builtin_amdgcn_fence(__ATOMIC_RELEASE, "agent");
;             asm volatile("s_waitcnt vmcnt(0)" ::: "memory");
;             const unsigned og = xb_add(&bar[XB_TOP], 1u);
;             const unsigned tg = og / nx;
;             if (og + 1u == (tg + 1u) * nx) xb_add(&bar[XB_TOPGEN], 1u);
;             else XB_SPIN(xb_ld(&bar[XB_TOPGEN]) == tg, bar);
;             __builtin_amdgcn_fence(__ATOMIC_ACQUIRE, "agent");
;             xb_add(&bar[XB_XGEN(b.x)], 1u);
.LBB0_388:
	s_andn2_saveexec_b64 s[0:1], s[42:43]
	s_cbranch_execz .LBB0_10
	s_mov_b64 s[42:43], exec
	s_lshl_b32 s0, 1, s76
	s_and_b32 s0, s0, 0x62c8
	s_cbranch_scc0 .Lgb_global
	v_readlane_b32 s0, v254, 38
	s_nop 1
	v_mov_b32_e32 v18, s0
	ds_read_b32 v19, v18 offset:8
	s_waitcnt lgkmcnt(0)
	v_readfirstlane_b32 s0, v19
	s_cmp_eq_u32 s0, 1
	s_cbranch_scc1 .LBB0_405
	s_cmp_eq_u32 s0, 2
	s_cbranch_scc1 .Lgb_global
	v_readlane_b32 s0, v254, 62
	v_readlane_b32 s1, v254, 63
	s_nop 1
	s_load_dwordx2 s[44:45], s[0:1], 0xa0
	s_waitcnt lgkmcnt(0)
	s_add_u32 s44, s44, 0xda04000
	s_addc_u32 s45, s45, 0
	v_mov_b32_e32 v20, 0
	global_load_dword v21, v20, s[44:45] sc1
	global_load_dword v22, v20, s[44:45] offset:256 sc1
	global_load_dword v23, v20, s[44:45] offset:512 sc1
	global_load_dword v24, v20, s[44:45] offset:768 sc1
	global_load_dword v25, v20, s[44:45] offset:1024 sc1
	global_load_dword v26, v20, s[44:45] offset:1280 sc1
	global_load_dword v27, v20, s[44:45] offset:1536 sc1
	global_load_dword v28, v20, s[44:45] offset:1792 sc1
	s_waitcnt vmcnt(0)
	v_add_u32_e32 v29, -1, v21
	v_and_b32_e32 v29, v29, v21
	v_mov_b32_e32 v30, v21
	v_add_u32_e32 v31, -1, v22
	v_and_b32_e32 v31, v31, v22
	v_or_b32_e32 v29, v29, v31
	v_min_u32_e32 v30, v30, v22
	v_add_u32_e32 v31, -1, v23
	v_and_b32_e32 v31, v31, v23
	v_or_b32_e32 v29, v29, v31
	v_min_u32_e32 v30, v30, v23
	v_add_u32_e32 v31, -1, v24
	v_and_b32_e32 v31, v31, v24
	v_or_b32_e32 v29, v29, v31
	v_min_u32_e32 v30, v30, v24
	v_add_u32_e32 v31, -1, v25
	v_and_b32_e32 v31, v31, v25
	v_or_b32_e32 v29, v29, v31
	v_min_u32_e32 v30, v30, v25
	v_add_u32_e32 v31, -1, v26
	v_and_b32_e32 v31, v31, v26
	v_or_b32_e32 v29, v29, v31
	v_min_u32_e32 v30, v30, v26
	v_add_u32_e32 v31, -1, v27
	v_and_b32_e32 v31, v31, v27
	v_or_b32_e32 v29, v29, v31
	v_min_u32_e32 v30, v30, v27
	v_add_u32_e32 v31, -1, v28
	v_and_b32_e32 v31, v31, v28
	v_or_b32_e32 v29, v29, v31
	v_min_u32_e32 v30, v30, v28
	v_cmp_eq_u32_e32 vcc, 0, v29
	v_cmp_ne_u32_e64 s[0:1], 0, v30
	s_nop 1
	s_and_b64 s[0:1], s[0:1], vcc
	s_and_b64 s[0:1], s[0:1], exec
	s_cselect_b32 s0, 1, 2
	v_mov_b32_e32 v19, s0
	ds_write_b32 v18, v19 offset:8
	s_waitcnt lgkmcnt(0)
	s_cmp_eq_u32 s0, 1
	s_cbranch_scc1 .LBB0_405
.Lgb_global:
	buffer_wbl2 sc1
	s_waitcnt lgkmcnt(0)
	s_waitcnt vmcnt(0)
	v_mbcnt_lo_u32_b32 v0, s42, 0
	v_mbcnt_hi_u32_b32 v0, s43, v0
	v_cmp_eq_u32_e32 vcc, 0, v0
	s_and_saveexec_b64 s[44:45], vcc
	s_cbranch_execz .LBB0_391
	s_bcnt1_i32_b64 s0, s[42:43]
	v_mov_b32_e32 v3, s0
	v_readlane_b32 s0, v254, 8
	v_readlane_b32 s1, v254, 9
	s_nop 4
	global_atomic_add v3, v1, v3, s[0:1] sc0
